# attention item prologue loads de-serialized; epilogue gate rows preloaded, subln read from an LDS copy
# speedup vs baseline: 1.0557x; 1.0110x over previous
; #define LAUNDER_TID(t) int t = (g_wave << 6) | (int)__builtin_amdgcn_mbcnt_hi(~0u, __builtin_amdgcn_mbcnt_lo(~0u, 0u)); asm volatile("" : "+v"(t))
; DI float wave_sum(float v) { for (int o = 32; o > 0; o >>= 1) v += __shfl_xor(v, o); return v; }
; DI void phase2(const Params& p, char* smem, const int g_wave) {
;   __shared__ int s_item;
;   __shared__ float s_lam;
;   const int wid = g_wave;
;   float lam;
;   {
;     const int lane = (int)__builtin_amdgcn_mbcnt_hi(~0u, __builtin_amdgcn_mbcnt_lo(~0u, 0u));
;     float a = p.lq1[lane] * p.lk1[lane], b = p.lq2[lane] * p.lk2[lane];
;     a = wave_sum(a); b = wave_sum(b);
;     lam = __expf(a) - __expf(b) + 0.2f;
;     if (lane == 0 && g_wave == 0) s_lam = lam;
;   }
;   int* ctr = (int*)(p.ws + WS_CTR);
;   constexpr int N0 = 128, N1 = N0 + 2048, N2 = N1 + 128, N3 = N2 + 64;
;   for (;;) {
;     { LAUNDER_TID(tq); if (tq == 0) s_item = atomicAdd(ctr, 1); }
;     __syncthreads();
;     const int it = __builtin_amdgcn_readfirstlane(s_item);
.LBB0_679:
	s_or_b64 exec, exec, s[0:1]
	s_and_b32 s0, s75, 0xffffffc0
	s_cmpk_lt_u32 s75, 0x80
	s_cselect_b32 s2, 17, 0
	s_lshr_b32 s28, s75, 7
	s_add_i32 s28, s28, 1
	s_cmpk_gt_u32 s75, 0xff
	s_cselect_b64 s[8:9], -1, 0
	s_lshl_b32 s29, s3, 3
	v_or_b32_e32 v196, s0, v2
	s_movk_i32 s6, 0x80
	v_cmp_gt_u32_e64 s[10:11], s6, v196
	s_and_saveexec_b64 s[4:5], s[10:11]
	v_lshlrev_b32_e32 v6, 2, v196
	global_load_dword v7, v6, s[44:45]
	v_add_u32_e32 v6, 0x24100, v6
	s_waitcnt vmcnt(0)
	ds_write_b32 v6, v7
	s_or_b64 exec, exec, s[4:5]
	s_sub_i32 s30, s29, 32
	s_lshl_b32 s0, s3, 4
	s_add_u32 s33, s72, 0x9641000
	s_addc_u32 s75, s73, 0
	v_writelane_b32 v255, s0, 9
	s_add_u32 s0, s72, 0x19741000
	v_writelane_b32 v255, s0, 17
	s_addc_u32 s0, s73, 0
	v_writelane_b32 v255, s0, 19
	s_add_u32 s0, s72, 0x11741000
	v_writelane_b32 v255, s0, 21
	s_addc_u32 s0, s73, 0
	v_writelane_b32 v255, s0, 23
	s_add_u32 s0, s72, 0x22841000
	v_writelane_b32 v255, s0, 10
	s_addc_u32 s0, s73, 0
	v_writelane_b32 v255, s0, 15
	s_add_u32 s0, s72, 0x1a841000
	v_writelane_b32 v255, s0, 11
	s_addc_u32 s0, s73, 0
	s_add_u32 s10, s72, 0x23941000
	s_addc_u32 s11, s73, 0
	v_writelane_b32 v255, s0, 13
	s_add_u32 s0, s70, 0x8100000
	s_addc_u32 s95, s71, 0
	s_add_u32 s16, s72, 0x239a3700
	s_addc_u32 s17, s73, 0
	s_add_u32 s18, s72, 0x239a5000
	v_writelane_b32 v255, s0, 12
	s_addc_u32 s19, s73, 0
	s_lshl_b32 s0, s3, 6
	s_add_i32 s96, s0, 16
	s_add_i32 s96, s96, 0xa100
	v_mov_b32_e32 v3, 0
	s_mov_b64 s[24:25], 0x80
	s_mov_b64 s[26:27], 0x20000
	s_mov_b32 s97, 0x3e38aa3b
	s_mov_b32 s3, 1.0
	s_mov_b32 s98, 0x800000
	s_add_i32 s99, 16, 0x1e700
	s_add_i32 s36, 16, 0x1f800
	s_movk_i32 s37, 0x90
	s_add_i32 s31, 16, 0x1ec00
	s_movk_i32 s86, 0x1900
	s_movk_i32 s87, 0x1000
	s_add_i32 s88, 16, 0x1c300
	s_movk_i32 s89, 0x7fff
	s_mov_b32 s90, 0x7060302
	s_add_i32 s91, 16, 0x1d500
	v_mov_b32_e32 v197, 0x3a27c5ac
	s_add_i32 s92, 16, 0x1a180
	s_add_i32 s93, 16, 0x18180
	s_add_i32 s94, 16, 0x100
	v_mov_b32_e32 v183, 1.0
	s_branch .LBB0_683

; #define LAS __attribute__((address_space(3)))
; DI void attn_item(const Params& p, char* smem, u16* qbase, const u16* gabase, const u16* kbase, const u16* vtbase,
;                   int tkv, int nkt, int mylimit, const float* lam_p, const int g_wave) {
;     ...
;   const int lane = tid & 63, wid = __builtin_amdgcn_readfirstlane(tid >> 6), r = lane & 31, hh = lane >> 5;
;   constexpr float C = 0.125f * 1.4426950408889634f;
;   LAS unsigned char* lds = (LAS unsigned char*)smem;
;   char* Kb = smem; char* Vb = smem + 2 * KBUF; char* Qs = smem + 2 * KBUF + 2 * VBUF + wid * QWAVE;
;   if (mylimit > 0) {
; #pragma unroll
;     for (int i = 0; i < 8; ++i) { const int id = i * 64 + lane, row = id >> 4, cc = id & 15;
;       *(uint4*)(Qs + row * 272 + cc * 16) = *(const uint4*)(qbase + (size_t)(wid * 32 + row) * 1024 + cc * 8); }
;   }
.LBB0_705:
	s_lshl_b32 s0, s50, 7
	s_and_b32 s4, s0, 0x380
	s_lshl_b64 s[0:1], s[42:43], 11
	s_add_u32 s0, s33, s0
	s_addc_u32 s1, s75, s1
	s_lshl_b32 s51, s4, 1
	s_add_u32 s0, s0, s51
	s_addc_u32 s1, s1, 0
	s_lshl_b32 s82, s78, 2
	s_add_i32 s34, s28, s82
	s_and_b64 s[4:5], s[54:55], exec
	v_mov_b32_e32 v4, v196
	s_cselect_b32 s78, s34, s2
	v_readfirstlane_b32 s4, v4
	s_ashr_i32 s80, s4, 6
	s_mul_i32 s4, s80, 0x2200
	s_add_i32 s81, s4, 16
	s_add_i32 s81, s81, 0x10000
	s_cmp_lg_u32 s78, 0
	v_and_b32_e32 v2, 63, v4
	s_cselect_b64 s[4:5], -1, 0
	v_lshlrev_b32_e32 v5, 4, v4
	s_and_b64 vcc, exec, s[4:5]
	v_and_b32_e32 v184, 0xf0, v5
	v_lshrrev_b32_e32 v6, 4, v2
	s_cbranch_vccz .LBB0_799
	v_lshrrev_b32_e32 v5, 4, v2
	v_lshl_or_b32 v14, s80, 5, v5
	v_mov_b32_e32 v185, v3
	v_ashrrev_i32_e32 v15, 31, v14
	v_lshl_add_u64 v[12:13], s[0:1], 0, v[184:185]
	v_lshlrev_b64 v[52:53], 11, v[14:15]
	v_lshl_add_u64 v[52:53], v[12:13], 0, v[52:53]
	global_load_dwordx4 v[20:23], v[52:53], off
	v_or_b32_e32 v54, 4, v14
	v_ashrrev_i32_e32 v55, 31, v54
	v_lshlrev_b64 v[54:55], 11, v[54:55]
	v_lshl_add_u64 v[54:55], v[12:13], 0, v[54:55]
	global_load_dwordx4 v[24:27], v[54:55], off
	v_or_b32_e32 v56, 8, v14
	v_ashrrev_i32_e32 v57, 31, v56
	v_lshlrev_b64 v[56:57], 11, v[56:57]
	v_lshl_add_u64 v[56:57], v[12:13], 0, v[56:57]
	global_load_dwordx4 v[28:31], v[56:57], off
	v_or_b32_e32 v58, 12, v14
	v_ashrrev_i32_e32 v59, 31, v58
	v_lshlrev_b64 v[58:59], 11, v[58:59]
	v_lshl_add_u64 v[58:59], v[12:13], 0, v[58:59]
	global_load_dwordx4 v[32:35], v[58:59], off
	v_or_b32_e32 v60, 16, v14
	v_ashrrev_i32_e32 v61, 31, v60
	v_lshlrev_b64 v[60:61], 11, v[60:61]
	v_lshl_add_u64 v[60:61], v[12:13], 0, v[60:61]
	global_load_dwordx4 v[36:39], v[60:61], off
	v_or_b32_e32 v62, 20, v14
	v_ashrrev_i32_e32 v63, 31, v62
	v_lshlrev_b64 v[62:63], 11, v[62:63]
	v_lshl_add_u64 v[62:63], v[12:13], 0, v[62:63]
	global_load_dwordx4 v[40:43], v[62:63], off
	v_or_b32_e32 v64, 24, v14
	v_ashrrev_i32_e32 v65, 31, v64
	v_lshlrev_b64 v[64:65], 11, v[64:65]
	v_lshl_add_u64 v[64:65], v[12:13], 0, v[64:65]
	global_load_dwordx4 v[44:47], v[64:65], off
	v_or_b32_e32 v66, 28, v14
	v_ashrrev_i32_e32 v67, 31, v66
	v_lshlrev_b64 v[66:67], 11, v[66:67]
	v_lshl_add_u64 v[66:67], v[12:13], 0, v[66:67]
	global_load_dwordx4 v[48:51], v[66:67], off
	v_mul_u32_u24_e32 v7, 0x110, v5
	v_add3_u32 v7, s81, v184, v7
	s_waitcnt vmcnt(7)
	ds_write_b128 v7, v[20:23]
	s_waitcnt vmcnt(6)
	ds_write_b128 v7, v[24:27] offset:1088
	s_waitcnt vmcnt(5)
	ds_write_b128 v7, v[28:31] offset:2176
	s_waitcnt vmcnt(4)
	ds_write_b128 v7, v[32:35] offset:3264
	s_waitcnt vmcnt(3)
	ds_write_b128 v7, v[36:39] offset:4352
	s_waitcnt vmcnt(2)
	ds_write_b128 v7, v[40:43] offset:5440
	s_waitcnt vmcnt(1)
	ds_write_b128 v7, v[44:47] offset:6528
	s_waitcnt vmcnt(0)
	ds_write_b128 v7, v[48:51] offset:7616
	s_cbranch_execnz .LBB0_708

; #define LAUNDER_TID(t) int t = (g_wave << 6) | (int)__builtin_amdgcn_mbcnt_hi(~0u, __builtin_amdgcn_mbcnt_lo(~0u, 0u)); asm volatile("" : "+v"(t))
; DI void attn_item(const Params& p, char* smem, u16* qbase, const u16* gabase, const u16* kbase, const u16* vtbase,
;                   int tkv, int nkt, int mylimit, const float* lam_p, const int g_wave) {
;     ...
;     asm volatile("s_waitcnt vmcnt(0)" ::: "memory");
;     __syncthreads();
;   }
;     ...
;   if (mylimit > 0) {
;     LAUNDER_TID(tid2);
;     const int lane = tid2 & 63, wid = tid2 >> 6, r = lane & 31, hh = lane >> 5;
;     u16* qrow = qbase + (size_t)(wid * 32 + r) * 1024;
;     { auto rr = __builtin_amdgcn_permlane32_swap(__float_as_uint(l0), __float_as_uint(l0), false, false);
;       l0 = __uint_as_float(rr[0]) + __uint_as_float(rr[1]); }
;     { auto rr = __builtin_amdgcn_permlane32_swap(__float_as_uint(l1), __float_as_uint(l1), false, false);
;       l1 = __uint_as_float(rr[0]) + __uint_as_float(rr[1]); }
;     const float i0 = 1.f / l0, i1 = *lam_p / l1;
;     float ss = 0.f;
; #pragma unroll
;     for (int d = 0; d < 4; ++d)
; #pragma unroll
;       for (int i = 0; i < 16; ++i) { float v = O0[d][i] * i0 - O1[d][i] * i1; O0[d][i] = v; ss += v * v; }
.LBB0_717:
	s_waitcnt vmcnt(0)
	s_addk_i32 s50, 0x4000
	v_lshl_add_u64 v[188:189], v[188:189], 0, s[24:25]
	v_lshl_add_u64 v[190:191], v[190:191], 0, s[24:25]
	v_lshl_add_u64 v[192:193], v[192:193], 0, s[26:27]
	s_cmp_eq_u32 s34, s54
	v_lshl_add_u64 v[194:195], v[194:195], 0, s[26:27]
	s_waitcnt vmcnt(0) lgkmcnt(0)
	s_barrier
	s_cbranch_scc0 .LBB0_709
	s_and_b64 vcc, exec, s[4:5]
	s_cbranch_vccz .LBB0_720
	s_lshl_b64 s[54:55], s[42:43], 1
	s_add_u32 s54, s70, s54
	s_addc_u32 s55, s71, s55
	s_add_u32 s54, s54, s51
	s_addc_u32 s55, s55, 0
	v_ashrrev_i32_e32 v252, 1, v196
	s_movk_i32 s32, 0xffe0
	v_bfi_b32 v252, s32, v252, v196
	v_mov_b32_e32 v253, 0
	v_lshlrev_b64 v[252:253], 11, v[252:253]
	v_lshl_add_u64 v[252:253], s[54:55], 0, v[252:253]
	v_lshrrev_b32_e32 v254, 3, v196
	v_and_b32_e32 v254, 4, v254
	v_lshlrev_b32_e32 v254, 1, v254
	v_mov_b32_e32 v216, v254
	v_mov_b32_e32 v217, 0
	v_lshl_add_u64 v[252:253], v[252:253], 0, v[216:217]
	global_load_dwordx2 v[220:221], v[252:253], off
	global_load_dwordx2 v[222:223], v[252:253], off offset:16
	global_load_dwordx2 v[224:225], v[252:253], off offset:32
	global_load_dwordx2 v[226:227], v[252:253], off offset:48
	global_load_dwordx2 v[228:229], v[252:253], off offset:64
	global_load_dwordx2 v[230:231], v[252:253], off offset:80
	global_load_dwordx2 v[232:233], v[252:253], off offset:96
	global_load_dwordx2 v[234:235], v[252:253], off offset:112
	global_load_dwordx2 v[236:237], v[252:253], off offset:128
	global_load_dwordx2 v[238:239], v[252:253], off offset:144
	global_load_dwordx2 v[240:241], v[252:253], off offset:160
	global_load_dwordx2 v[242:243], v[252:253], off offset:176
	global_load_dwordx2 v[244:245], v[252:253], off offset:192
	global_load_dwordx2 v[246:247], v[252:253], off offset:208
	global_load_dwordx2 v[248:249], v[252:253], off offset:224
	global_load_dwordx2 v[250:251], v[252:253], off offset:240
	v_mov_b32_e32 v2, v196
	ds_read_b32 v8, v3
	v_mov_b32_e32 v6, v186
	v_mov_b32_e32 v7, v187
	s_nop 0
	v_permlane32_swap_b32_e32 v186, v6
	v_permlane32_swap_b32_e32 v187, v7
	v_ashrrev_i32_e32 v4, 1, v2
	s_movk_i32 s34, 0xffe0
	v_pk_add_f32 v[6:7], v[186:187], v[6:7]
	v_bfi_b32 v4, s34, v4, v2
	s_waitcnt lgkmcnt(0)
	v_div_scale_f32 v9, s[34:35], v7, v7, v8
	v_rcp_f32_e32 v10, v9
	s_lshl_b64 s[4:5], s[42:43], 1
	s_add_u32 s4, s70, s4
	s_addc_u32 s5, s71, s5
	v_fma_f32 v11, -v9, v10, 1.0
	v_fmac_f32_e32 v10, v11, v10
	v_div_scale_f32 v11, vcc, v8, v7, v8
	v_mul_f32_e32 v12, v11, v10
	v_fma_f32 v13, -v9, v12, v11
	v_fmac_f32_e32 v12, v13, v10
	v_fma_f32 v9, -v9, v12, v11
	v_div_fmas_f32 v9, v9, v10, v12
	v_div_fixup_f32 v7, v9, v7, v8
	v_div_scale_f32 v8, s[34:35], v6, v6, 1.0
	v_rcp_f32_e32 v9, v8
	s_add_u32 s4, s4, s51
	v_ashrrev_i32_e32 v5, 31, v4
	v_lshrrev_b32_e32 v2, 3, v2
	v_fma_f32 v10, -v8, v9, 1.0
	v_fmac_f32_e32 v9, v10, v9
	v_div_scale_f32 v10, vcc, 1.0, v6, 1.0
	v_mul_f32_e32 v11, v10, v9
	v_fma_f32 v12, -v8, v11, v10
	v_fmac_f32_e32 v11, v12, v9
	v_fma_f32 v8, -v8, v11, v10
	v_div_fmas_f32 v8, v8, v9, v11
	v_div_fixup_f32 v6, v8, v6, 1.0
	v_mov_b32_e32 v8, v130
	v_mov_b32_e32 v9, v114
	v_mul_f32_e32 v10, v114, v7
	v_pk_fma_f32 v[170:171], v[8:9], v[6:7], v[10:11] op_sel_hi:[1,1,0] neg_lo:[0,0,1] neg_hi:[0,0,1]
	v_mov_b32_e32 v10, v132
	v_mov_b32_e32 v11, v116
	v_mul_f32_e32 v12, v116, v7
	v_mov_b32_e32 v114, v131
	v_mul_f32_e32 v8, v115, v7
	v_pk_fma_f32 v[166:167], v[10:11], v[6:7], v[12:13] op_sel_hi:[1,1,0] neg_lo:[0,0,1] neg_hi:[0,0,1]
	v_mov_b32_e32 v116, v133
	v_mul_f32_e32 v10, v117, v7
	v_pk_fma_f32 v[168:169], v[114:115], v[6:7], v[8:9] op_sel_hi:[1,1,0] neg_lo:[0,0,1] neg_hi:[0,0,1]
	v_pk_fma_f32 v[164:165], v[116:117], v[6:7], v[10:11] op_sel_hi:[1,1,0] neg_lo:[0,0,1] neg_hi:[0,0,1]
	v_mov_b32_e32 v10, v134
	v_mov_b32_e32 v11, v118
	v_mul_f32_e32 v12, v118, v7
	v_pk_mul_f32 v[8:9], v[168:169], v[168:169]
	v_pk_fma_f32 v[162:163], v[10:11], v[6:7], v[12:13] op_sel_hi:[1,1,0] neg_lo:[0,0,1] neg_hi:[0,0,1]
	v_mov_b32_e32 v118, v135
	v_mul_f32_e32 v10, v119, v7
	v_pk_fma_f32 v[8:9], v[170:171], v[170:171], v[8:9]
	v_pk_fma_f32 v[160:161], v[118:119], v[6:7], v[10:11] op_sel_hi:[1,1,0] neg_lo:[0,0,1] neg_hi:[0,0,1]
	v_mov_b32_e32 v10, v136
	v_mov_b32_e32 v11, v120
	v_mul_f32_e32 v12, v120, v7
	v_pk_fma_f32 v[8:9], v[166:167], v[166:167], v[8:9]
	v_pk_fma_f32 v[158:159], v[10:11], v[6:7], v[12:13] op_sel_hi:[1,1,0] neg_lo:[0,0,1] neg_hi:[0,0,1]
	v_mov_b32_e32 v120, v137
	v_mul_f32_e32 v10, v121, v7
	v_pk_fma_f32 v[8:9], v[164:165], v[164:165], v[8:9]
	v_pk_fma_f32 v[156:157], v[120:121], v[6:7], v[10:11] op_sel_hi:[1,1,0] neg_lo:[0,0,1] neg_hi:[0,0,1]
	v_mov_b32_e32 v10, v138
	v_mov_b32_e32 v11, v122
	v_mul_f32_e32 v12, v122, v7
	v_pk_fma_f32 v[8:9], v[162:163], v[162:163], v[8:9]
	v_pk_fma_f32 v[154:155], v[10:11], v[6:7], v[12:13] op_sel_hi:[1,1,0] neg_lo:[0,0,1] neg_hi:[0,0,1]
	v_mov_b32_e32 v122, v139
	v_mul_f32_e32 v10, v123, v7
	v_pk_fma_f32 v[8:9], v[160:161], v[160:161], v[8:9]
	v_pk_fma_f32 v[152:153], v[122:123], v[6:7], v[10:11] op_sel_hi:[1,1,0] neg_lo:[0,0,1] neg_hi:[0,0,1]
	v_mov_b32_e32 v10, v140
	v_mov_b32_e32 v11, v124
	v_mul_f32_e32 v12, v124, v7
	v_pk_fma_f32 v[8:9], v[158:159], v[158:159], v[8:9]
	v_pk_fma_f32 v[150:151], v[10:11], v[6:7], v[12:13] op_sel_hi:[1,1,0] neg_lo:[0,0,1] neg_hi:[0,0,1]
	v_mov_b32_e32 v124, v141
	v_mul_f32_e32 v10, v125, v7
	v_pk_fma_f32 v[8:9], v[156:157], v[156:157], v[8:9]
	v_pk_fma_f32 v[148:149], v[124:125], v[6:7], v[10:11] op_sel_hi:[1,1,0] neg_lo:[0,0,1] neg_hi:[0,0,1]
	v_mov_b32_e32 v10, v142
	v_mov_b32_e32 v11, v126
	v_mul_f32_e32 v12, v126, v7
	v_pk_fma_f32 v[8:9], v[154:155], v[154:155], v[8:9]
; DI void attn_item(const Params& p, char* smem, u16* qbase, const u16* gabase, const u16* kbase, const u16* vtbase,
;                   int tkv, int nkt, int mylimit, const float* lam_p, const int g_wave) {
;     ...
;     for (int d = 0; d < 4; ++d)
; #pragma unroll
;       for (int i = 0; i < 16; ++i) { float v = O0[d][i] * i0 - O1[d][i] * i1; O0[d][i] = v; ss += v * v; }
	v_pk_fma_f32 v[146:147], v[10:11], v[6:7], v[12:13] op_sel_hi:[1,1,0] neg_lo:[0,0,1] neg_hi:[0,0,1]
	v_mov_b32_e32 v126, v143
	v_mul_f32_e32 v10, v127, v7
	v_pk_fma_f32 v[8:9], v[152:153], v[152:153], v[8:9]
	v_pk_fma_f32 v[140:141], v[126:127], v[6:7], v[10:11] op_sel_hi:[1,1,0] neg_lo:[0,0,1] neg_hi:[0,0,1]
	v_mov_b32_e32 v10, v144
	v_mov_b32_e32 v11, v128
	v_mul_f32_e32 v12, v128, v7
	v_pk_fma_f32 v[8:9], v[150:151], v[150:151], v[8:9]
	v_pk_fma_f32 v[138:139], v[10:11], v[6:7], v[12:13] op_sel_hi:[1,1,0] neg_lo:[0,0,1] neg_hi:[0,0,1]
	v_mov_b32_e32 v128, v145
	v_mul_f32_e32 v10, v129, v7
	v_pk_fma_f32 v[8:9], v[148:149], v[148:149], v[8:9]
	v_pk_fma_f32 v[136:137], v[128:129], v[6:7], v[10:11] op_sel_hi:[1,1,0] neg_lo:[0,0,1] neg_hi:[0,0,1]
	v_mov_b32_e32 v10, v98
	v_mov_b32_e32 v11, v82
	v_mul_f32_e32 v12, v82, v7
	v_pk_fma_f32 v[8:9], v[146:147], v[146:147], v[8:9]
	v_pk_fma_f32 v[134:135], v[10:11], v[6:7], v[12:13] op_sel_hi:[1,1,0] neg_lo:[0,0,1] neg_hi:[0,0,1]
	v_mov_b32_e32 v82, v99
	v_mul_f32_e32 v10, v83, v7
	v_pk_fma_f32 v[8:9], v[140:141], v[140:141], v[8:9]
	v_pk_fma_f32 v[132:133], v[82:83], v[6:7], v[10:11] op_sel_hi:[1,1,0] neg_lo:[0,0,1] neg_hi:[0,0,1]
	v_mov_b32_e32 v10, v100
	v_mov_b32_e32 v11, v84
	v_mul_f32_e32 v12, v84, v7
	v_pk_fma_f32 v[8:9], v[138:139], v[138:139], v[8:9]
	v_pk_fma_f32 v[130:131], v[10:11], v[6:7], v[12:13] op_sel_hi:[1,1,0] neg_lo:[0,0,1] neg_hi:[0,0,1]
	v_mov_b32_e32 v84, v101
	v_mul_f32_e32 v10, v85, v7
	v_pk_fma_f32 v[8:9], v[136:137], v[136:137], v[8:9]
	v_pk_fma_f32 v[128:129], v[84:85], v[6:7], v[10:11] op_sel_hi:[1,1,0] neg_lo:[0,0,1] neg_hi:[0,0,1]
	v_mov_b32_e32 v10, v102
	v_mov_b32_e32 v11, v86
	v_mul_f32_e32 v12, v86, v7
	v_pk_fma_f32 v[8:9], v[134:135], v[134:135], v[8:9]
	v_pk_fma_f32 v[126:127], v[10:11], v[6:7], v[12:13] op_sel_hi:[1,1,0] neg_lo:[0,0,1] neg_hi:[0,0,1]
	v_mov_b32_e32 v86, v103
	v_mul_f32_e32 v10, v87, v7
	v_pk_fma_f32 v[8:9], v[132:133], v[132:133], v[8:9]
	v_pk_fma_f32 v[124:125], v[86:87], v[6:7], v[10:11] op_sel_hi:[1,1,0] neg_lo:[0,0,1] neg_hi:[0,0,1]
	v_mov_b32_e32 v10, v104
	v_mov_b32_e32 v11, v88
	v_mul_f32_e32 v12, v88, v7
	v_pk_fma_f32 v[8:9], v[130:131], v[130:131], v[8:9]
	v_pk_fma_f32 v[122:123], v[10:11], v[6:7], v[12:13] op_sel_hi:[1,1,0] neg_lo:[0,0,1] neg_hi:[0,0,1]
	v_mov_b32_e32 v88, v105
	v_mul_f32_e32 v10, v89, v7
	v_pk_fma_f32 v[8:9], v[128:129], v[128:129], v[8:9]
	v_pk_fma_f32 v[120:121], v[88:89], v[6:7], v[10:11] op_sel_hi:[1,1,0] neg_lo:[0,0,1] neg_hi:[0,0,1]
	v_mov_b32_e32 v10, v106
	v_mov_b32_e32 v11, v90
	v_mul_f32_e32 v12, v90, v7
	v_pk_fma_f32 v[8:9], v[126:127], v[126:127], v[8:9]
	v_pk_fma_f32 v[118:119], v[10:11], v[6:7], v[12:13] op_sel_hi:[1,1,0] neg_lo:[0,0,1] neg_hi:[0,0,1]
	v_mov_b32_e32 v90, v107
	v_mul_f32_e32 v10, v91, v7
	v_pk_fma_f32 v[8:9], v[124:125], v[124:125], v[8:9]
	v_pk_fma_f32 v[116:117], v[90:91], v[6:7], v[10:11] op_sel_hi:[1,1,0] neg_lo:[0,0,1] neg_hi:[0,0,1]
	v_mov_b32_e32 v10, v108
	v_mov_b32_e32 v11, v92
	v_mul_f32_e32 v12, v92, v7
	v_pk_fma_f32 v[8:9], v[122:123], v[122:123], v[8:9]
	v_pk_fma_f32 v[114:115], v[10:11], v[6:7], v[12:13] op_sel_hi:[1,1,0] neg_lo:[0,0,1] neg_hi:[0,0,1]
	v_mov_b32_e32 v92, v109
	v_mul_f32_e32 v10, v93, v7
	v_pk_fma_f32 v[8:9], v[120:121], v[120:121], v[8:9]
	v_pk_fma_f32 v[108:109], v[92:93], v[6:7], v[10:11] op_sel_hi:[1,1,0] neg_lo:[0,0,1] neg_hi:[0,0,1]
	v_mov_b32_e32 v10, v110
	v_mov_b32_e32 v11, v94
	v_mul_f32_e32 v12, v94, v7
	v_pk_fma_f32 v[8:9], v[118:119], v[118:119], v[8:9]
	v_pk_fma_f32 v[106:107], v[10:11], v[6:7], v[12:13] op_sel_hi:[1,1,0] neg_lo:[0,0,1] neg_hi:[0,0,1]
	v_mov_b32_e32 v94, v111
	v_mul_f32_e32 v10, v95, v7
	v_pk_fma_f32 v[8:9], v[116:117], v[116:117], v[8:9]
	v_pk_fma_f32 v[104:105], v[94:95], v[6:7], v[10:11] op_sel_hi:[1,1,0] neg_lo:[0,0,1] neg_hi:[0,0,1]
	v_mov_b32_e32 v10, v112
	v_mov_b32_e32 v11, v96
	v_mul_f32_e32 v12, v96, v7
	v_pk_fma_f32 v[8:9], v[114:115], v[114:115], v[8:9]
	v_pk_fma_f32 v[102:103], v[10:11], v[6:7], v[12:13] op_sel_hi:[1,1,0] neg_lo:[0,0,1] neg_hi:[0,0,1]
	v_mov_b32_e32 v96, v113
	v_mul_f32_e32 v10, v97, v7
	v_pk_fma_f32 v[8:9], v[108:109], v[108:109], v[8:9]
	v_pk_fma_f32 v[100:101], v[96:97], v[6:7], v[10:11] op_sel_hi:[1,1,0] neg_lo:[0,0,1] neg_hi:[0,0,1]
	v_mov_b32_e32 v10, v66
	v_mov_b32_e32 v11, v50
	v_mul_f32_e32 v12, v50, v7
	v_pk_fma_f32 v[8:9], v[106:107], v[106:107], v[8:9]
	v_pk_fma_f32 v[98:99], v[10:11], v[6:7], v[12:13] op_sel_hi:[1,1,0] neg_lo:[0,0,1] neg_hi:[0,0,1]
	v_mov_b32_e32 v50, v67
	v_mul_f32_e32 v10, v51, v7
	v_pk_fma_f32 v[8:9], v[104:105], v[104:105], v[8:9]
	v_pk_fma_f32 v[96:97], v[50:51], v[6:7], v[10:11] op_sel_hi:[1,1,0] neg_lo:[0,0,1] neg_hi:[0,0,1]
	v_mov_b32_e32 v10, v68
	v_mov_b32_e32 v11, v52
	v_mul_f32_e32 v12, v52, v7
	v_pk_fma_f32 v[8:9], v[102:103], v[102:103], v[8:9]
	v_pk_fma_f32 v[94:95], v[10:11], v[6:7], v[12:13] op_sel_hi:[1,1,0] neg_lo:[0,0,1] neg_hi:[0,0,1]
	v_mov_b32_e32 v52, v69
	v_mul_f32_e32 v10, v53, v7
	v_pk_fma_f32 v[8:9], v[100:101], v[100:101], v[8:9]
	v_pk_fma_f32 v[92:93], v[52:53], v[6:7], v[10:11] op_sel_hi:[1,1,0] neg_lo:[0,0,1] neg_hi:[0,0,1]
	v_mov_b32_e32 v10, v70
	v_mov_b32_e32 v11, v54
	v_mul_f32_e32 v12, v54, v7
	v_pk_fma_f32 v[8:9], v[98:99], v[98:99], v[8:9]
	v_pk_fma_f32 v[90:91], v[10:11], v[6:7], v[12:13] op_sel_hi:[1,1,0] neg_lo:[0,0,1] neg_hi:[0,0,1]
	v_mov_b32_e32 v54, v71
	v_mul_f32_e32 v10, v55, v7
	v_pk_fma_f32 v[8:9], v[96:97], v[96:97], v[8:9]
	v_pk_fma_f32 v[88:89], v[54:55], v[6:7], v[10:11] op_sel_hi:[1,1,0] neg_lo:[0,0,1] neg_hi:[0,0,1]
	v_mov_b32_e32 v10, v72
	v_mov_b32_e32 v11, v56
	v_mul_f32_e32 v12, v56, v7
; DI void attn_item(const Params& p, char* smem, u16* qbase, const u16* gabase, const u16* kbase, const u16* vtbase,
;                   int tkv, int nkt, int mylimit, const float* lam_p, const int g_wave) {
;     ...
;     const float i0 = 1.f / l0, i1 = *lam_p / l1;
;     float ss = 0.f;
; #pragma unroll
;     for (int d = 0; d < 4; ++d)
; #pragma unroll
;       for (int i = 0; i < 16; ++i) { float v = O0[d][i] * i0 - O1[d][i] * i1; O0[d][i] = v; ss += v * v; }
;     { auto rr = __builtin_amdgcn_permlane32_swap(__float_as_uint(ss), __float_as_uint(ss), false, false);
;       ss = __uint_as_float(rr[0]) + __uint_as_float(rr[1]); }
;     const float rs = rsqrtf(ss * (1.f / 128.f) + 1e-5f) * 0.8f;
;     const u16* garow = gabase + (size_t)(wid * 32 + r) * 1024;
	v_pk_fma_f32 v[8:9], v[94:95], v[94:95], v[8:9]
	v_pk_fma_f32 v[86:87], v[10:11], v[6:7], v[12:13] op_sel_hi:[1,1,0] neg_lo:[0,0,1] neg_hi:[0,0,1]
	v_mov_b32_e32 v56, v73
	v_mul_f32_e32 v10, v57, v7
	v_pk_fma_f32 v[8:9], v[92:93], v[92:93], v[8:9]
	v_pk_fma_f32 v[84:85], v[56:57], v[6:7], v[10:11] op_sel_hi:[1,1,0] neg_lo:[0,0,1] neg_hi:[0,0,1]
	v_mov_b32_e32 v10, v74
	v_mov_b32_e32 v11, v58
	v_mul_f32_e32 v12, v58, v7
	v_pk_fma_f32 v[8:9], v[90:91], v[90:91], v[8:9]
	v_pk_fma_f32 v[82:83], v[10:11], v[6:7], v[12:13] op_sel_hi:[1,1,0] neg_lo:[0,0,1] neg_hi:[0,0,1]
	v_mov_b32_e32 v58, v75
	v_mul_f32_e32 v10, v59, v7
	v_pk_fma_f32 v[8:9], v[88:89], v[88:89], v[8:9]
	v_pk_fma_f32 v[72:73], v[58:59], v[6:7], v[10:11] op_sel_hi:[1,1,0] neg_lo:[0,0,1] neg_hi:[0,0,1]
	v_mov_b32_e32 v10, v76
	v_mov_b32_e32 v11, v60
	v_mul_f32_e32 v12, v60, v7
	v_pk_fma_f32 v[8:9], v[86:87], v[86:87], v[8:9]
	v_pk_fma_f32 v[70:71], v[10:11], v[6:7], v[12:13] op_sel_hi:[1,1,0] neg_lo:[0,0,1] neg_hi:[0,0,1]
	v_mov_b32_e32 v60, v77
	v_mul_f32_e32 v10, v61, v7
	v_pk_fma_f32 v[8:9], v[84:85], v[84:85], v[8:9]
	v_pk_fma_f32 v[68:69], v[60:61], v[6:7], v[10:11] op_sel_hi:[1,1,0] neg_lo:[0,0,1] neg_hi:[0,0,1]
	v_mov_b32_e32 v10, v78
	v_mov_b32_e32 v11, v62
	v_mul_f32_e32 v12, v62, v7
	v_pk_fma_f32 v[8:9], v[82:83], v[82:83], v[8:9]
	v_pk_fma_f32 v[66:67], v[10:11], v[6:7], v[12:13] op_sel_hi:[1,1,0] neg_lo:[0,0,1] neg_hi:[0,0,1]
	v_mov_b32_e32 v62, v79
	v_mul_f32_e32 v10, v63, v7
	v_pk_fma_f32 v[8:9], v[72:73], v[72:73], v[8:9]
	v_pk_fma_f32 v[62:63], v[62:63], v[6:7], v[10:11] op_sel_hi:[1,1,0] neg_lo:[0,0,1] neg_hi:[0,0,1]
	v_mov_b32_e32 v10, v80
	v_mov_b32_e32 v11, v64
	v_mul_f32_e32 v12, v64, v7
	v_pk_fma_f32 v[8:9], v[70:71], v[70:71], v[8:9]
	v_pk_fma_f32 v[60:61], v[10:11], v[6:7], v[12:13] op_sel_hi:[1,1,0] neg_lo:[0,0,1] neg_hi:[0,0,1]
	v_mov_b32_e32 v64, v81
	v_mul_f32_e32 v10, v65, v7
	v_pk_fma_f32 v[8:9], v[68:69], v[68:69], v[8:9]
	v_pk_fma_f32 v[58:59], v[64:65], v[6:7], v[10:11] op_sel_hi:[1,1,0] neg_lo:[0,0,1] neg_hi:[0,0,1]
	v_mov_b32_e32 v10, v34
	v_mov_b32_e32 v11, v18
	v_mul_f32_e32 v12, v18, v7
	v_pk_fma_f32 v[8:9], v[66:67], v[66:67], v[8:9]
	v_pk_fma_f32 v[56:57], v[10:11], v[6:7], v[12:13] op_sel_hi:[1,1,0] neg_lo:[0,0,1] neg_hi:[0,0,1]
	v_mov_b32_e32 v18, v35
	v_mul_f32_e32 v10, v19, v7
	v_pk_fma_f32 v[8:9], v[62:63], v[62:63], v[8:9]
	v_pk_fma_f32 v[54:55], v[18:19], v[6:7], v[10:11] op_sel_hi:[1,1,0] neg_lo:[0,0,1] neg_hi:[0,0,1]
	v_mov_b32_e32 v10, v36
	v_mov_b32_e32 v11, v20
	v_mul_f32_e32 v12, v20, v7
	v_pk_fma_f32 v[8:9], v[60:61], v[60:61], v[8:9]
	v_pk_fma_f32 v[52:53], v[10:11], v[6:7], v[12:13] op_sel_hi:[1,1,0] neg_lo:[0,0,1] neg_hi:[0,0,1]
	v_mov_b32_e32 v20, v37
	v_mul_f32_e32 v10, v21, v7
	v_pk_fma_f32 v[8:9], v[58:59], v[58:59], v[8:9]
	v_pk_fma_f32 v[50:51], v[20:21], v[6:7], v[10:11] op_sel_hi:[1,1,0] neg_lo:[0,0,1] neg_hi:[0,0,1]
	v_mov_b32_e32 v10, v38
	v_mov_b32_e32 v11, v22
	v_mul_f32_e32 v12, v22, v7
	v_pk_fma_f32 v[8:9], v[56:57], v[56:57], v[8:9]
	v_pk_fma_f32 v[36:37], v[10:11], v[6:7], v[12:13] op_sel_hi:[1,1,0] neg_lo:[0,0,1] neg_hi:[0,0,1]
	v_mov_b32_e32 v22, v39
	v_mul_f32_e32 v10, v23, v7
	v_pk_fma_f32 v[8:9], v[54:55], v[54:55], v[8:9]
	v_pk_fma_f32 v[34:35], v[22:23], v[6:7], v[10:11] op_sel_hi:[1,1,0] neg_lo:[0,0,1] neg_hi:[0,0,1]
	v_mov_b32_e32 v10, v40
	v_mov_b32_e32 v11, v24
	v_mul_f32_e32 v12, v24, v7
	v_pk_fma_f32 v[8:9], v[52:53], v[52:53], v[8:9]
	v_pk_fma_f32 v[22:23], v[10:11], v[6:7], v[12:13] op_sel_hi:[1,1,0] neg_lo:[0,0,1] neg_hi:[0,0,1]
	v_mov_b32_e32 v24, v41
	v_mul_f32_e32 v10, v25, v7
	v_pk_fma_f32 v[8:9], v[50:51], v[50:51], v[8:9]
	v_pk_fma_f32 v[20:21], v[24:25], v[6:7], v[10:11] op_sel_hi:[1,1,0] neg_lo:[0,0,1] neg_hi:[0,0,1]
	v_mov_b32_e32 v10, v42
	v_mov_b32_e32 v11, v26
	v_mul_f32_e32 v12, v26, v7
	v_pk_fma_f32 v[8:9], v[36:37], v[36:37], v[8:9]
	v_pk_fma_f32 v[16:17], v[10:11], v[6:7], v[12:13] op_sel_hi:[1,1,0] neg_lo:[0,0,1] neg_hi:[0,0,1]
	v_mov_b32_e32 v26, v43
	v_mul_f32_e32 v10, v27, v7
	v_pk_fma_f32 v[8:9], v[34:35], v[34:35], v[8:9]
	v_pk_fma_f32 v[14:15], v[26:27], v[6:7], v[10:11] op_sel_hi:[1,1,0] neg_lo:[0,0,1] neg_hi:[0,0,1]
	v_mov_b32_e32 v10, v44
	v_mov_b32_e32 v11, v28
	v_mov_b32_e32 v28, v45
	v_pk_fma_f32 v[8:9], v[22:23], v[22:23], v[8:9]
	v_pk_mul_f32 v[10:11], v[10:11], v[6:7]
	v_pk_mul_f32 v[12:13], v[28:29], v[6:7]
	v_pk_fma_f32 v[8:9], v[20:21], v[20:21], v[8:9]
	v_mov_b32_e32 v18, v12
	v_mov_b32_e32 v19, v10
	v_mov_b32_e32 v10, v13
	v_pk_fma_f32 v[8:9], v[16:17], v[16:17], v[8:9]
	v_pk_add_f32 v[12:13], v[18:19], v[10:11] neg_lo:[0,1] neg_hi:[0,1]
	v_pk_fma_f32 v[8:9], v[14:15], v[14:15], v[8:9]
	v_mul_f32_e32 v10, v13, v13
	v_pk_add_f32 v[8:9], v[10:11], v[8:9] op_sel_hi:[0,1]
	v_mov_b32_e32 v10, v46
	v_mov_b32_e32 v11, v30
	v_mov_b32_e32 v30, v47
	v_pk_mul_f32 v[10:11], v[10:11], v[6:7]
	v_pk_mul_f32 v[18:19], v[30:31], v[6:7]
	v_mov_b32_e32 v25, v10
	v_mov_b32_e32 v24, v18
	v_mov_b32_e32 v10, v19
	v_pk_add_f32 v[10:11], v[24:25], v[10:11] neg_lo:[0,1] neg_hi:[0,1]
	v_pk_fma_f32 v[8:9], v[12:13], v[12:13], v[8:9]
	v_mul_f32_e32 v18, v11, v11
	v_pk_add_f32 v[8:9], v[18:19], v[8:9] op_sel_hi:[0,1]
	v_pk_fma_f32 v[18:19], v[10:11], v[10:11], v[8:9]
	v_mov_b32_e32 v8, v48
	v_mov_b32_e32 v9, v32
	v_mov_b32_e32 v32, v49
	v_pk_mul_f32 v[8:9], v[8:9], v[6:7]
	v_pk_mul_f32 v[6:7], v[32:33], v[6:7]
	v_mov_b32_e32 v25, v8
	v_mov_b32_e32 v24, v6
	v_mov_b32_e32 v8, v7
	v_pk_add_f32 v[8:9], v[24:25], v[8:9] neg_lo:[0,1] neg_hi:[0,1]
	s_addc_u32 s5, s5, 0
	v_mul_f32_e32 v6, v9, v9
	v_pk_add_f32 v[6:7], v[6:7], v[18:19] op_sel_hi:[0,1]
	v_pk_fma_f32 v[6:7], v[8:9], v[8:9], v[6:7]
	v_lshlrev_b64 v[4:5], 11, v[4:5]
	v_mov_b32_e32 v7, v6
	s_nop 1
	v_permlane32_swap_b32_e32 v6, v7
	v_add_f32_e32 v6, v6, v7
	v_mov_b32_e32 v7, 0x3727c5ac
	v_fmamk_f32 v6, v6, 0x3c000000, v7
	v_cmp_gt_f32_e32 vcc, s98, v6
	v_mul_f32_e32 v7, 0x4b800000, v6
	v_lshl_add_u64 v[24:25], s[0:1], 0, v[4:5]
	v_cndmask_b32_e32 v6, v6, v7, vcc
	v_rsq_f32_e32 v6, v6
	v_lshl_add_u64 v[4:5], s[4:5], 0, v[4:5]
	v_mul_f32_e32 v7, 0x45800000, v6
	v_cndmask_b32_e32 v6, v6, v7, vcc
	v_mul_f32_e32 v15, 0x3f4ccccd, v6
	v_and_b32_e32 v6, 4, v2
	v_lshlrev_b32_e32 v2, 1, v6
	v_lshl_add_u64 v[18:19], v[4:5], 0, v[2:3]
	s_waitcnt vmcnt(0)
; DI u32 cvtpk(float lo, float hi) { u32 r; asm volatile("v_cvt_pk_bf16_f32 %0, %1, %2" : "=v"(r) : "v"(lo), "v"(hi)); return r; }
; DI float silu(float x) { return x * __builtin_amdgcn_rcpf(1.f + __expf(-x)); }
; DI void attn_item(const Params& p, char* smem, u16* qbase, const u16* gabase, const u16* kbase, const u16* vtbase,
;                   int tkv, int nkt, int mylimit, const float* lam_p, const int g_wave) {
;     ...
;     const u16* garow = gabase + (size_t)(wid * 32 + r) * 1024;
; #pragma unroll
;     for (int d = 0; d < 4; ++d)
; #pragma unroll
;       for (int g = 0; g < 4; ++g) {
;         int dv = 32 * d + 8 * g + 4 * hh;
;         u32x2 gg = *(const u32x2*)(garow + dv);
;         float4 sl = *(const float4*)(p.subln + dv);
;         float g0 = __uint_as_float(gg[0] << 16), g1 = __uint_as_float(gg[0] & 0xffff0000u), g2 = __uint_as_float(gg[1] << 16), g3 = __uint_as_float(gg[1] & 0xffff0000u);
;         float o0 = O0[d][4 * g + 0] * rs * sl.x * silu(g0);
;         float o1 = O0[d][4 * g + 1] * rs * sl.y * silu(g1);
;         float o2 = O0[d][4 * g + 2] * rs * sl.z * silu(g2);
;         float o3 = O0[d][4 * g + 3] * rs * sl.w * silu(g3);
;         u32x2 o; o[0] = cvtpk(o0, o1); o[1] = cvtpk(o2, o3);
;         *(u32x2*)(qrow + dv) = o;
;       }
	v_mov_b32_e32 v26, v220
	v_mov_b32_e32 v27, v221
	v_lshlrev_b32_e32 v17, 2, v6
	v_add_u32_e32 v219, 0x24100, v17
	ds_read_b128 v[4:7], v219
	v_mul_f32_e32 v31, v166, v15
	v_mul_f32_e32 v33, v164, v15
	v_mul_f32_e32 v29, v170, v15
	v_mul_f32_e32 v20, v20, v15
	v_mul_f32_e32 v12, v12, v15
	v_mul_f32_e32 v10, v10, v15
	v_mul_f32_e32 v8, v8, v15
	v_lshlrev_b32_e32 v28, 16, v26
	v_and_b32_e32 v26, 0xffff0000, v26
	s_waitcnt lgkmcnt(0)
	v_mov_b32_e32 v39, v4
	v_mul_f32_e32 v4, 0xbfb8aa3b, v26
	v_exp_f32_e32 v4, v4
	v_lshlrev_b32_e32 v30, 16, v27
	v_and_b32_e32 v32, 0xffff0000, v27
	v_mul_f32_e32 v27, v168, v15
	v_add_f32_e32 v4, 1.0, v4
	v_rcp_f32_e32 v4, v4
	v_mul_f32_e32 v21, 0xbfb8aa3b, v28
	v_exp_f32_e32 v21, v21
	v_pk_mul_f32 v[4:5], v[4:5], v[26:27]
	s_nop 0
	v_mul_f32_e32 v23, v4, v5
	v_mul_f32_e32 v4, 0xbfb8aa3b, v30
	v_exp_f32_e32 v4, v4
	v_mov_b32_e32 v5, v6
	v_add_f32_e32 v21, 1.0, v21
	v_rcp_f32_e32 v38, v21
	v_add_f32_e32 v4, 1.0, v4
	v_rcp_f32_e32 v4, v4
	v_pk_mul_f32 v[28:29], v[38:39], v[28:29]
	s_nop 0
	v_mul_f32_e32 v21, v28, v29
	v_pk_mul_f32 v[4:5], v[4:5], v[30:31]
	v_mul_f32_e32 v28, v162, v15
	v_mul_f32_e32 v26, v4, v5
	v_mul_f32_e32 v4, 0xbfb8aa3b, v32
	v_exp_f32_e32 v4, v4
	v_mul_f32_e32 v30, v160, v15
	v_add_f32_e32 v4, 1.0, v4
	v_rcp_f32_e32 v6, v4
	s_nop 0
	v_pk_mul_f32 v[4:5], v[6:7], v[32:33]
	s_nop 0
	v_mul_f32_e32 v4, v4, v5
	v_cvt_pk_bf16_f32 v6, v21, v23
	v_cvt_pk_bf16_f32 v7, v26, v4
	v_lshl_add_u64 v[4:5], v[24:25], 0, v[2:3]
	global_store_dwordx2 v[4:5], v[6:7], off
	v_mov_b32_e32 v6, v222
	v_mov_b32_e32 v7, v223
	s_nop 0
	ds_read_b128 v[24:27], v219 offset:32
	v_lshlrev_b32_e32 v29, 16, v6
	v_mul_f32_e32 v2, 0xbfb8aa3b, v29
	v_exp_f32_e32 v2, v2
	v_and_b32_e32 v31, 0xffff0000, v6
	v_mul_f32_e32 v6, 0xbfb8aa3b, v31
	v_exp_f32_e32 v6, v6
	v_add_f32_e32 v2, 1.0, v2
	v_rcp_f32_e32 v39, v2
	s_waitcnt lgkmcnt(0)
	v_mov_b32_e32 v38, v24
	v_lshlrev_b32_e32 v33, 16, v7
	v_add_f32_e32 v6, 1.0, v6
	v_pk_mul_f32 v[28:29], v[38:39], v[28:29]
	v_and_b32_e32 v7, 0xffff0000, v7
	v_mul_f32_e32 v2, v28, v29
	v_rcp_f32_e32 v29, v6
	v_mul_f32_e32 v6, 0xbfb8aa3b, v33
	v_exp_f32_e32 v6, v6
	v_mov_b32_e32 v28, v25
	v_pk_mul_f32 v[24:25], v[28:29], v[30:31]
	v_mov_b32_e32 v32, v26
	v_add_f32_e32 v6, 1.0, v6
	v_mul_f32_e32 v21, v24, v25
	v_rcp_f32_e32 v25, v6
	v_mul_f32_e32 v6, 0xbfb8aa3b, v7
	v_exp_f32_e32 v6, v6
	v_mul_f32_e32 v24, v158, v15
	v_pk_mul_f32 v[24:25], v[24:25], v[32:33]
	v_mul_f32_e32 v38, v154, v15
	v_add_f32_e32 v6, 1.0, v6
	v_mul_f32_e32 v23, v24, v25
	v_rcp_f32_e32 v25, v6
	v_mul_f32_e32 v24, v156, v15
	v_mov_b32_e32 v6, v27
	v_pk_mul_f32 v[6:7], v[24:25], v[6:7]
	s_nop 0
	v_mul_f32_e32 v7, v6, v7
	v_cvt_pk_bf16_f32 v6, v2, v21
	v_cvt_pk_bf16_f32 v7, v23, v7
	global_store_dwordx2 v[4:5], v[6:7], off offset:16
	v_mov_b32_e32 v6, v224
	v_mov_b32_e32 v7, v225
	s_nop 0
	ds_read_b128 v[24:27], v219 offset:64
	v_lshlrev_b32_e32 v29, 16, v6
	v_mul_f32_e32 v2, 0xbfb8aa3b, v29
	v_exp_f32_e32 v2, v2
	v_and_b32_e32 v31, 0xffff0000, v6
	v_mul_f32_e32 v6, 0xbfb8aa3b, v31
	v_exp_f32_e32 v6, v6
	v_add_f32_e32 v2, 1.0, v2
	v_rcp_f32_e32 v39, v2
	s_waitcnt lgkmcnt(0)
	v_mov_b32_e32 v28, v24
	v_lshlrev_b32_e32 v33, 16, v7
	v_add_f32_e32 v6, 1.0, v6
	v_pk_mul_f32 v[28:29], v[38:39], v[28:29]
	v_mov_b32_e32 v30, v25
	v_mul_f32_e32 v2, v28, v29
	v_rcp_f32_e32 v29, v6
	v_mul_f32_e32 v6, 0xbfb8aa3b, v33
	v_exp_f32_e32 v6, v6
	v_mul_f32_e32 v28, v152, v15
	v_and_b32_e32 v7, 0xffff0000, v7
	v_pk_mul_f32 v[24:25], v[28:29], v[30:31]
	v_add_f32_e32 v6, 1.0, v6
	v_mul_f32_e32 v21, v24, v25
	v_rcp_f32_e32 v25, v6
	v_mul_f32_e32 v6, 0xbfb8aa3b, v7
	v_exp_f32_e32 v6, v6
	v_mul_f32_e32 v24, v150, v15
	v_mov_b32_e32 v32, v26
	v_pk_mul_f32 v[24:25], v[24:25], v[32:33]
	v_add_f32_e32 v6, 1.0, v6
	v_mul_f32_e32 v23, v24, v25
	v_rcp_f32_e32 v25, v6
	v_mul_f32_e32 v24, v148, v15
	v_mov_b32_e32 v6, v27
	v_mul_f32_e32 v38, v146, v15
	v_pk_mul_f32 v[6:7], v[24:25], v[6:7]
	s_nop 0
	v_mul_f32_e32 v7, v6, v7
	v_cvt_pk_bf16_f32 v6, v2, v21
	v_cvt_pk_bf16_f32 v7, v23, v7
	global_store_dwordx2 v[4:5], v[6:7], off offset:32
	v_mov_b32_e32 v6, v226
	v_mov_b32_e32 v7, v227
	s_nop 0
	ds_read_b128 v[24:27], v219 offset:96
	v_lshlrev_b32_e32 v29, 16, v6
	v_mul_f32_e32 v2, 0xbfb8aa3b, v29
	v_exp_f32_e32 v2, v2
	v_and_b32_e32 v31, 0xffff0000, v6
	v_mul_f32_e32 v6, 0xbfb8aa3b, v31
	v_exp_f32_e32 v6, v6
	v_add_f32_e32 v2, 1.0, v2
	v_rcp_f32_e32 v39, v2
	s_waitcnt lgkmcnt(0)
	v_mov_b32_e32 v28, v24
	v_lshlrev_b32_e32 v33, 16, v7
	v_add_f32_e32 v6, 1.0, v6
	v_pk_mul_f32 v[28:29], v[38:39], v[28:29]
	v_mov_b32_e32 v30, v25
	v_mul_f32_e32 v2, v28, v29
	v_rcp_f32_e32 v29, v6
	v_mul_f32_e32 v6, 0xbfb8aa3b, v33
	v_exp_f32_e32 v6, v6
	v_mul_f32_e32 v28, v140, v15
	v_and_b32_e32 v7, 0xffff0000, v7
	v_pk_mul_f32 v[24:25], v[28:29], v[30:31]
	v_add_f32_e32 v6, 1.0, v6
	v_mul_f32_e32 v21, v24, v25
	v_rcp_f32_e32 v25, v6
	v_mul_f32_e32 v6, 0xbfb8aa3b, v7
	v_exp_f32_e32 v6, v6
	v_mul_f32_e32 v24, v138, v15
	v_mov_b32_e32 v32, v26
	v_pk_mul_f32 v[24:25], v[24:25], v[32:33]
	v_add_f32_e32 v6, 1.0, v6
	v_mul_f32_e32 v23, v24, v25
	v_rcp_f32_e32 v25, v6
	v_mul_f32_e32 v24, v136, v15
	v_mov_b32_e32 v6, v27
	v_mul_f32_e32 v38, v134, v15
	v_pk_mul_f32 v[6:7], v[24:25], v[6:7]
	s_nop 0
	v_mul_f32_e32 v7, v6, v7
	v_cvt_pk_bf16_f32 v6, v2, v21
	v_cvt_pk_bf16_f32 v7, v23, v7
	global_store_dwordx2 v[4:5], v[6:7], off offset:48
	v_mov_b32_e32 v6, v228
	v_mov_b32_e32 v7, v229
	s_nop 0
	ds_read_b128 v[24:27], v219 offset:128
	v_lshlrev_b32_e32 v29, 16, v6
	v_mul_f32_e32 v2, 0xbfb8aa3b, v29
	v_exp_f32_e32 v2, v2
	v_and_b32_e32 v31, 0xffff0000, v6
	v_mul_f32_e32 v6, 0xbfb8aa3b, v31
	v_exp_f32_e32 v6, v6
	v_add_f32_e32 v2, 1.0, v2
	v_rcp_f32_e32 v39, v2
	s_waitcnt lgkmcnt(0)
; DI u32 cvtpk(float lo, float hi) { u32 r; asm volatile("v_cvt_pk_bf16_f32 %0, %1, %2" : "=v"(r) : "v"(lo), "v"(hi)); return r; }
; DI float silu(float x) { return x * __builtin_amdgcn_rcpf(1.f + __expf(-x)); }
; DI void attn_item(const Params& p, char* smem, u16* qbase, const u16* gabase, const u16* kbase, const u16* vtbase,
;                   int tkv, int nkt, int mylimit, const float* lam_p, const int g_wave) {
;     ...
;     const u16* garow = gabase + (size_t)(wid * 32 + r) * 1024;
; #pragma unroll
;     for (int d = 0; d < 4; ++d)
; #pragma unroll
;       for (int g = 0; g < 4; ++g) {
;         int dv = 32 * d + 8 * g + 4 * hh;
;         u32x2 gg = *(const u32x2*)(garow + dv);
;         float4 sl = *(const float4*)(p.subln + dv);
;         float g0 = __uint_as_float(gg[0] << 16), g1 = __uint_as_float(gg[0] & 0xffff0000u), g2 = __uint_as_float(gg[1] << 16), g3 = __uint_as_float(gg[1] & 0xffff0000u);
;         float o0 = O0[d][4 * g + 0] * rs * sl.x * silu(g0);
;         float o1 = O0[d][4 * g + 1] * rs * sl.y * silu(g1);
;         float o2 = O0[d][4 * g + 2] * rs * sl.z * silu(g2);
;         float o3 = O0[d][4 * g + 3] * rs * sl.w * silu(g3);
;         u32x2 o; o[0] = cvtpk(o0, o1); o[1] = cvtpk(o2, o3);
;         *(u32x2*)(qrow + dv) = o;
;       }
	v_mov_b32_e32 v28, v24
	v_lshlrev_b32_e32 v33, 16, v7
	v_add_f32_e32 v6, 1.0, v6
	v_pk_mul_f32 v[28:29], v[38:39], v[28:29]
	v_mov_b32_e32 v30, v25
	v_mul_f32_e32 v2, v28, v29
	v_rcp_f32_e32 v29, v6
	v_mul_f32_e32 v6, 0xbfb8aa3b, v33
	v_exp_f32_e32 v6, v6
	v_mul_f32_e32 v28, v132, v15
	v_and_b32_e32 v7, 0xffff0000, v7
	v_pk_mul_f32 v[24:25], v[28:29], v[30:31]
	v_add_f32_e32 v6, 1.0, v6
	v_mul_f32_e32 v21, v24, v25
	v_rcp_f32_e32 v25, v6
	v_mul_f32_e32 v6, 0xbfb8aa3b, v7
	v_exp_f32_e32 v6, v6
	v_mul_f32_e32 v24, v130, v15
	v_mov_b32_e32 v32, v26
	v_pk_mul_f32 v[24:25], v[24:25], v[32:33]
	v_add_f32_e32 v6, 1.0, v6
	v_mul_f32_e32 v23, v24, v25
	v_rcp_f32_e32 v25, v6
	v_mul_f32_e32 v24, v128, v15
	v_mov_b32_e32 v6, v27
	v_mul_f32_e32 v38, v126, v15
	v_pk_mul_f32 v[6:7], v[24:25], v[6:7]
	s_nop 0
	v_mul_f32_e32 v7, v6, v7
	v_cvt_pk_bf16_f32 v6, v2, v21
	v_cvt_pk_bf16_f32 v7, v23, v7
	global_store_dwordx2 v[4:5], v[6:7], off offset:64
	v_mov_b32_e32 v6, v230
	v_mov_b32_e32 v7, v231
	s_nop 0
	ds_read_b128 v[24:27], v219 offset:160
	v_lshlrev_b32_e32 v29, 16, v6
	v_mul_f32_e32 v2, 0xbfb8aa3b, v29
	v_exp_f32_e32 v2, v2
	v_and_b32_e32 v31, 0xffff0000, v6
	v_mul_f32_e32 v6, 0xbfb8aa3b, v31
	v_exp_f32_e32 v6, v6
	v_add_f32_e32 v2, 1.0, v2
	v_rcp_f32_e32 v39, v2
	s_waitcnt lgkmcnt(0)
	v_mov_b32_e32 v28, v24
	v_lshlrev_b32_e32 v33, 16, v7
	v_add_f32_e32 v6, 1.0, v6
	v_pk_mul_f32 v[28:29], v[38:39], v[28:29]
	v_mov_b32_e32 v30, v25
	v_mul_f32_e32 v2, v28, v29
	v_rcp_f32_e32 v29, v6
	v_mul_f32_e32 v6, 0xbfb8aa3b, v33
	v_exp_f32_e32 v6, v6
	v_mul_f32_e32 v28, v124, v15
	v_and_b32_e32 v7, 0xffff0000, v7
	v_pk_mul_f32 v[24:25], v[28:29], v[30:31]
	v_add_f32_e32 v6, 1.0, v6
	v_mul_f32_e32 v21, v24, v25
	v_rcp_f32_e32 v25, v6
	v_mul_f32_e32 v6, 0xbfb8aa3b, v7
	v_exp_f32_e32 v6, v6
	v_mul_f32_e32 v24, v122, v15
	v_mov_b32_e32 v32, v26
	v_pk_mul_f32 v[24:25], v[24:25], v[32:33]
	v_add_f32_e32 v6, 1.0, v6
	v_mul_f32_e32 v23, v24, v25
	v_rcp_f32_e32 v25, v6
	v_mul_f32_e32 v24, v120, v15
	v_mov_b32_e32 v6, v27
	v_mul_f32_e32 v38, v118, v15
	v_pk_mul_f32 v[6:7], v[24:25], v[6:7]
	s_nop 0
	v_mul_f32_e32 v7, v6, v7
	v_cvt_pk_bf16_f32 v6, v2, v21
	v_cvt_pk_bf16_f32 v7, v23, v7
	global_store_dwordx2 v[4:5], v[6:7], off offset:80
	v_mov_b32_e32 v6, v232
	v_mov_b32_e32 v7, v233
	s_nop 0
	ds_read_b128 v[24:27], v219 offset:192
	v_lshlrev_b32_e32 v29, 16, v6
	v_mul_f32_e32 v2, 0xbfb8aa3b, v29
	v_exp_f32_e32 v2, v2
	v_and_b32_e32 v31, 0xffff0000, v6
	v_mul_f32_e32 v6, 0xbfb8aa3b, v31
	v_exp_f32_e32 v6, v6
	v_add_f32_e32 v2, 1.0, v2
	v_rcp_f32_e32 v39, v2
	s_waitcnt lgkmcnt(0)
	v_mov_b32_e32 v28, v24
	v_lshlrev_b32_e32 v33, 16, v7
	v_add_f32_e32 v6, 1.0, v6
	v_pk_mul_f32 v[28:29], v[38:39], v[28:29]
	v_mov_b32_e32 v30, v25
	v_mul_f32_e32 v2, v28, v29
	v_rcp_f32_e32 v29, v6
	v_mul_f32_e32 v6, 0xbfb8aa3b, v33
	v_exp_f32_e32 v6, v6
	v_mul_f32_e32 v28, v116, v15
	v_and_b32_e32 v7, 0xffff0000, v7
	v_pk_mul_f32 v[24:25], v[28:29], v[30:31]
	v_add_f32_e32 v6, 1.0, v6
	v_mul_f32_e32 v21, v24, v25
	v_rcp_f32_e32 v25, v6
	v_mul_f32_e32 v6, 0xbfb8aa3b, v7
	v_exp_f32_e32 v6, v6
	v_mul_f32_e32 v24, v114, v15
	v_mov_b32_e32 v32, v26
	v_pk_mul_f32 v[24:25], v[24:25], v[32:33]
	v_add_f32_e32 v6, 1.0, v6
	v_mul_f32_e32 v23, v24, v25
	v_rcp_f32_e32 v25, v6
	v_mul_f32_e32 v24, v108, v15
	v_mov_b32_e32 v6, v27
	v_mul_f32_e32 v38, v106, v15
	v_pk_mul_f32 v[6:7], v[24:25], v[6:7]
	s_nop 0
	v_mul_f32_e32 v7, v6, v7
	v_cvt_pk_bf16_f32 v6, v2, v21
	v_cvt_pk_bf16_f32 v7, v23, v7
	global_store_dwordx2 v[4:5], v[6:7], off offset:96
	v_mov_b32_e32 v6, v234
	v_mov_b32_e32 v7, v235
	s_nop 0
	ds_read_b128 v[24:27], v219 offset:224
	v_lshlrev_b32_e32 v29, 16, v6
	v_mul_f32_e32 v2, 0xbfb8aa3b, v29
	v_exp_f32_e32 v2, v2
	v_and_b32_e32 v31, 0xffff0000, v6
	v_mul_f32_e32 v6, 0xbfb8aa3b, v31
	v_exp_f32_e32 v6, v6
	v_add_f32_e32 v2, 1.0, v2
	v_rcp_f32_e32 v39, v2
	s_waitcnt lgkmcnt(0)
	v_mov_b32_e32 v28, v24
	v_lshlrev_b32_e32 v33, 16, v7
	v_add_f32_e32 v6, 1.0, v6
	v_pk_mul_f32 v[28:29], v[38:39], v[28:29]
	v_mov_b32_e32 v30, v25
	v_mul_f32_e32 v2, v28, v29
	v_rcp_f32_e32 v29, v6
	v_mul_f32_e32 v6, 0xbfb8aa3b, v33
	v_exp_f32_e32 v6, v6
	v_mul_f32_e32 v28, v104, v15
	v_and_b32_e32 v7, 0xffff0000, v7
	v_pk_mul_f32 v[24:25], v[28:29], v[30:31]
	v_add_f32_e32 v6, 1.0, v6
	v_mul_f32_e32 v21, v24, v25
	v_rcp_f32_e32 v25, v6
	v_mul_f32_e32 v6, 0xbfb8aa3b, v7
	v_exp_f32_e32 v6, v6
	v_mul_f32_e32 v24, v102, v15
	v_mov_b32_e32 v32, v26
	v_pk_mul_f32 v[24:25], v[24:25], v[32:33]
	v_add_f32_e32 v6, 1.0, v6
	v_mul_f32_e32 v23, v24, v25
	v_rcp_f32_e32 v25, v6
	v_mul_f32_e32 v24, v100, v15
	v_mov_b32_e32 v6, v27
	v_mul_f32_e32 v38, v98, v15
	v_pk_mul_f32 v[6:7], v[24:25], v[6:7]
	s_nop 0
	v_mul_f32_e32 v7, v6, v7
	v_cvt_pk_bf16_f32 v6, v2, v21
	v_cvt_pk_bf16_f32 v7, v23, v7
	global_store_dwordx2 v[4:5], v[6:7], off offset:112
	v_mov_b32_e32 v6, v236
	v_mov_b32_e32 v7, v237
	s_nop 0
	ds_read_b128 v[24:27], v219 offset:256
	v_lshlrev_b32_e32 v29, 16, v6
	v_mul_f32_e32 v2, 0xbfb8aa3b, v29
	v_exp_f32_e32 v2, v2
	v_and_b32_e32 v31, 0xffff0000, v6
	v_mul_f32_e32 v6, 0xbfb8aa3b, v31
	v_exp_f32_e32 v6, v6
	v_add_f32_e32 v2, 1.0, v2
	v_rcp_f32_e32 v39, v2
	s_waitcnt lgkmcnt(0)
; DI u32 cvtpk(float lo, float hi) { u32 r; asm volatile("v_cvt_pk_bf16_f32 %0, %1, %2" : "=v"(r) : "v"(lo), "v"(hi)); return r; }
; DI float silu(float x) { return x * __builtin_amdgcn_rcpf(1.f + __expf(-x)); }
; DI void attn_item(const Params& p, char* smem, u16* qbase, const u16* gabase, const u16* kbase, const u16* vtbase,
;                   int tkv, int nkt, int mylimit, const float* lam_p, const int g_wave) {
;     ...
;     const u16* garow = gabase + (size_t)(wid * 32 + r) * 1024;
; #pragma unroll
;     for (int d = 0; d < 4; ++d)
; #pragma unroll
;       for (int g = 0; g < 4; ++g) {
;         int dv = 32 * d + 8 * g + 4 * hh;
;         u32x2 gg = *(const u32x2*)(garow + dv);
;         float4 sl = *(const float4*)(p.subln + dv);
;         float g0 = __uint_as_float(gg[0] << 16), g1 = __uint_as_float(gg[0] & 0xffff0000u), g2 = __uint_as_float(gg[1] << 16), g3 = __uint_as_float(gg[1] & 0xffff0000u);
;         float o0 = O0[d][4 * g + 0] * rs * sl.x * silu(g0);
;         float o1 = O0[d][4 * g + 1] * rs * sl.y * silu(g1);
;         float o2 = O0[d][4 * g + 2] * rs * sl.z * silu(g2);
;         float o3 = O0[d][4 * g + 3] * rs * sl.w * silu(g3);
;         u32x2 o; o[0] = cvtpk(o0, o1); o[1] = cvtpk(o2, o3);
;         *(u32x2*)(qrow + dv) = o;
;       }
	v_mov_b32_e32 v28, v24
	v_lshlrev_b32_e32 v33, 16, v7
	v_add_f32_e32 v6, 1.0, v6
	v_pk_mul_f32 v[28:29], v[38:39], v[28:29]
	v_mov_b32_e32 v30, v25
	v_mul_f32_e32 v2, v28, v29
	v_rcp_f32_e32 v29, v6
	v_mul_f32_e32 v6, 0xbfb8aa3b, v33
	v_exp_f32_e32 v6, v6
	v_mul_f32_e32 v28, v96, v15
	v_and_b32_e32 v7, 0xffff0000, v7
	v_pk_mul_f32 v[24:25], v[28:29], v[30:31]
	v_add_f32_e32 v6, 1.0, v6
	v_mul_f32_e32 v21, v24, v25
	v_rcp_f32_e32 v25, v6
	v_mul_f32_e32 v6, 0xbfb8aa3b, v7
	v_exp_f32_e32 v6, v6
	v_mul_f32_e32 v24, v94, v15
	v_mov_b32_e32 v32, v26
	v_pk_mul_f32 v[24:25], v[24:25], v[32:33]
	v_add_f32_e32 v6, 1.0, v6
	v_mul_f32_e32 v23, v24, v25
	v_rcp_f32_e32 v25, v6
	v_mul_f32_e32 v24, v92, v15
	v_mov_b32_e32 v6, v27
	v_mul_f32_e32 v38, v90, v15
	v_pk_mul_f32 v[6:7], v[24:25], v[6:7]
	s_nop 0
	v_mul_f32_e32 v7, v6, v7
	v_cvt_pk_bf16_f32 v6, v2, v21
	v_cvt_pk_bf16_f32 v7, v23, v7
	global_store_dwordx2 v[4:5], v[6:7], off offset:128
	v_mov_b32_e32 v6, v238
	v_mov_b32_e32 v7, v239
	s_nop 0
	ds_read_b128 v[24:27], v219 offset:288
	v_lshlrev_b32_e32 v29, 16, v6
	v_mul_f32_e32 v2, 0xbfb8aa3b, v29
	v_exp_f32_e32 v2, v2
	v_and_b32_e32 v31, 0xffff0000, v6
	v_mul_f32_e32 v6, 0xbfb8aa3b, v31
	v_exp_f32_e32 v6, v6
	v_add_f32_e32 v2, 1.0, v2
	v_rcp_f32_e32 v39, v2
	s_waitcnt lgkmcnt(0)
	v_mov_b32_e32 v28, v24
	v_lshlrev_b32_e32 v33, 16, v7
	v_add_f32_e32 v6, 1.0, v6
	v_pk_mul_f32 v[28:29], v[38:39], v[28:29]
	v_mov_b32_e32 v30, v25
	v_mul_f32_e32 v2, v28, v29
	v_rcp_f32_e32 v29, v6
	v_mul_f32_e32 v6, 0xbfb8aa3b, v33
	v_exp_f32_e32 v6, v6
	v_mul_f32_e32 v28, v88, v15
	v_and_b32_e32 v7, 0xffff0000, v7
	v_pk_mul_f32 v[24:25], v[28:29], v[30:31]
	v_add_f32_e32 v6, 1.0, v6
	v_mul_f32_e32 v21, v24, v25
	v_rcp_f32_e32 v25, v6
	v_mul_f32_e32 v6, 0xbfb8aa3b, v7
	v_exp_f32_e32 v6, v6
	v_mul_f32_e32 v24, v86, v15
	v_mov_b32_e32 v32, v26
	v_pk_mul_f32 v[24:25], v[24:25], v[32:33]
	v_add_f32_e32 v6, 1.0, v6
	v_mul_f32_e32 v23, v24, v25
	v_rcp_f32_e32 v25, v6
	v_mul_f32_e32 v24, v84, v15
	v_mov_b32_e32 v6, v27
	v_mul_f32_e32 v38, v82, v15
	v_pk_mul_f32 v[6:7], v[24:25], v[6:7]
	s_nop 0
	v_mul_f32_e32 v7, v6, v7
	v_cvt_pk_bf16_f32 v6, v2, v21
	v_cvt_pk_bf16_f32 v7, v23, v7
	global_store_dwordx2 v[4:5], v[6:7], off offset:144
	v_mov_b32_e32 v6, v240
	v_mov_b32_e32 v7, v241
	s_nop 0
	ds_read_b128 v[24:27], v219 offset:320
	v_lshlrev_b32_e32 v29, 16, v6
	v_mul_f32_e32 v2, 0xbfb8aa3b, v29
	v_exp_f32_e32 v2, v2
	v_and_b32_e32 v31, 0xffff0000, v6
	v_mul_f32_e32 v6, 0xbfb8aa3b, v31
	v_exp_f32_e32 v6, v6
	v_add_f32_e32 v2, 1.0, v2
	v_rcp_f32_e32 v39, v2
	s_waitcnt lgkmcnt(0)
	v_mov_b32_e32 v28, v24
	v_lshlrev_b32_e32 v33, 16, v7
	v_add_f32_e32 v6, 1.0, v6
	v_pk_mul_f32 v[28:29], v[38:39], v[28:29]
	v_mov_b32_e32 v30, v25
	v_mul_f32_e32 v2, v28, v29
	v_rcp_f32_e32 v29, v6
	v_mul_f32_e32 v6, 0xbfb8aa3b, v33
	v_exp_f32_e32 v6, v6
	v_mul_f32_e32 v28, v72, v15
	v_and_b32_e32 v7, 0xffff0000, v7
	v_pk_mul_f32 v[24:25], v[28:29], v[30:31]
	v_add_f32_e32 v6, 1.0, v6
	v_mul_f32_e32 v21, v24, v25
	v_rcp_f32_e32 v25, v6
	v_mul_f32_e32 v6, 0xbfb8aa3b, v7
	v_exp_f32_e32 v6, v6
	v_mul_f32_e32 v24, v70, v15
	v_mov_b32_e32 v32, v26
	v_pk_mul_f32 v[24:25], v[24:25], v[32:33]
	v_add_f32_e32 v6, 1.0, v6
	v_mul_f32_e32 v23, v24, v25
	v_rcp_f32_e32 v25, v6
	v_mul_f32_e32 v24, v68, v15
	v_mov_b32_e32 v6, v27
	v_mul_f32_e32 v38, v66, v15
	v_pk_mul_f32 v[6:7], v[24:25], v[6:7]
	s_nop 0
	v_mul_f32_e32 v7, v6, v7
	v_cvt_pk_bf16_f32 v6, v2, v21
	v_cvt_pk_bf16_f32 v7, v23, v7
	global_store_dwordx2 v[4:5], v[6:7], off offset:160
	v_mov_b32_e32 v6, v242
	v_mov_b32_e32 v7, v243
	s_nop 0
	ds_read_b128 v[24:27], v219 offset:352
	v_lshlrev_b32_e32 v29, 16, v6
	v_mul_f32_e32 v2, 0xbfb8aa3b, v29
	v_exp_f32_e32 v2, v2
	v_and_b32_e32 v31, 0xffff0000, v6
	v_mul_f32_e32 v6, 0xbfb8aa3b, v31
	v_exp_f32_e32 v6, v6
	v_add_f32_e32 v2, 1.0, v2
	v_rcp_f32_e32 v39, v2
	s_waitcnt lgkmcnt(0)
	v_mov_b32_e32 v28, v24
	v_lshlrev_b32_e32 v33, 16, v7
	v_add_f32_e32 v6, 1.0, v6
	v_pk_mul_f32 v[28:29], v[38:39], v[28:29]
	v_mov_b32_e32 v30, v25
	v_mul_f32_e32 v2, v28, v29
	v_rcp_f32_e32 v29, v6
	v_mul_f32_e32 v6, 0xbfb8aa3b, v33
	v_exp_f32_e32 v6, v6
	v_mul_f32_e32 v28, v62, v15
	v_and_b32_e32 v7, 0xffff0000, v7
	v_pk_mul_f32 v[24:25], v[28:29], v[30:31]
	v_add_f32_e32 v6, 1.0, v6
	v_mul_f32_e32 v21, v24, v25
	v_rcp_f32_e32 v25, v6
	v_mul_f32_e32 v6, 0xbfb8aa3b, v7
	v_exp_f32_e32 v6, v6
	v_mul_f32_e32 v24, v60, v15
	v_mov_b32_e32 v32, v26
	v_pk_mul_f32 v[24:25], v[24:25], v[32:33]
	v_add_f32_e32 v6, 1.0, v6
	v_mul_f32_e32 v23, v24, v25
	v_rcp_f32_e32 v25, v6
	v_mul_f32_e32 v24, v58, v15
	v_mov_b32_e32 v6, v27
	v_mul_f32_e32 v38, v56, v15
	v_pk_mul_f32 v[6:7], v[24:25], v[6:7]
	s_nop 0
	v_mul_f32_e32 v7, v6, v7
	v_cvt_pk_bf16_f32 v6, v2, v21
	v_cvt_pk_bf16_f32 v7, v23, v7
	global_store_dwordx2 v[4:5], v[6:7], off offset:176
	v_mov_b32_e32 v6, v244
	v_mov_b32_e32 v7, v245
	s_nop 0
	ds_read_b128 v[24:27], v219 offset:384
	v_lshlrev_b32_e32 v29, 16, v6
	v_mul_f32_e32 v2, 0xbfb8aa3b, v29
	v_exp_f32_e32 v2, v2
	v_and_b32_e32 v31, 0xffff0000, v6
	v_mul_f32_e32 v6, 0xbfb8aa3b, v31
	v_exp_f32_e32 v6, v6
	v_add_f32_e32 v2, 1.0, v2
	v_rcp_f32_e32 v39, v2
	s_waitcnt lgkmcnt(0)
; DI u32 cvtpk(float lo, float hi) { u32 r; asm volatile("v_cvt_pk_bf16_f32 %0, %1, %2" : "=v"(r) : "v"(lo), "v"(hi)); return r; }
; DI float silu(float x) { return x * __builtin_amdgcn_rcpf(1.f + __expf(-x)); }
; DI void attn_item(const Params& p, char* smem, u16* qbase, const u16* gabase, const u16* kbase, const u16* vtbase,
;                   int tkv, int nkt, int mylimit, const float* lam_p, const int g_wave) {
;     ...
;     const u16* garow = gabase + (size_t)(wid * 32 + r) * 1024;
; #pragma unroll
;     for (int d = 0; d < 4; ++d)
; #pragma unroll
;       for (int g = 0; g < 4; ++g) {
;         int dv = 32 * d + 8 * g + 4 * hh;
;         u32x2 gg = *(const u32x2*)(garow + dv);
;         float4 sl = *(const float4*)(p.subln + dv);
;         float g0 = __uint_as_float(gg[0] << 16), g1 = __uint_as_float(gg[0] & 0xffff0000u), g2 = __uint_as_float(gg[1] << 16), g3 = __uint_as_float(gg[1] & 0xffff0000u);
;         float o0 = O0[d][4 * g + 0] * rs * sl.x * silu(g0);
;         float o1 = O0[d][4 * g + 1] * rs * sl.y * silu(g1);
;         float o2 = O0[d][4 * g + 2] * rs * sl.z * silu(g2);
;         float o3 = O0[d][4 * g + 3] * rs * sl.w * silu(g3);
;         u32x2 o; o[0] = cvtpk(o0, o1); o[1] = cvtpk(o2, o3);
;         *(u32x2*)(qrow + dv) = o;
;       }
	v_mov_b32_e32 v28, v24
	v_lshlrev_b32_e32 v33, 16, v7
	v_add_f32_e32 v6, 1.0, v6
	v_pk_mul_f32 v[28:29], v[38:39], v[28:29]
	v_mov_b32_e32 v30, v25
	v_mul_f32_e32 v2, v28, v29
	v_rcp_f32_e32 v29, v6
	v_mul_f32_e32 v6, 0xbfb8aa3b, v33
	v_exp_f32_e32 v6, v6
	v_mul_f32_e32 v28, v54, v15
	v_and_b32_e32 v7, 0xffff0000, v7
	v_pk_mul_f32 v[24:25], v[28:29], v[30:31]
	v_add_f32_e32 v6, 1.0, v6
	v_mul_f32_e32 v21, v24, v25
	v_rcp_f32_e32 v25, v6
	v_mul_f32_e32 v6, 0xbfb8aa3b, v7
	v_exp_f32_e32 v6, v6
	v_mul_f32_e32 v24, v52, v15
	v_mov_b32_e32 v32, v26
	v_pk_mul_f32 v[24:25], v[24:25], v[32:33]
	v_add_f32_e32 v6, 1.0, v6
	v_mul_f32_e32 v23, v24, v25
	v_rcp_f32_e32 v25, v6
	v_mul_f32_e32 v24, v50, v15
	v_mov_b32_e32 v6, v27
	v_mul_f32_e32 v32, v36, v15
	v_pk_mul_f32 v[6:7], v[24:25], v[6:7]
	s_nop 0
	v_mul_f32_e32 v7, v6, v7
	v_cvt_pk_bf16_f32 v6, v2, v21
	v_cvt_pk_bf16_f32 v7, v23, v7
	global_store_dwordx2 v[4:5], v[6:7], off offset:192
	v_mov_b32_e32 v6, v246
	v_mov_b32_e32 v7, v247
	s_nop 0
	ds_read_b128 v[24:27], v219 offset:416
	v_lshlrev_b32_e32 v29, 16, v6
	v_mul_f32_e32 v2, 0xbfb8aa3b, v29
	v_exp_f32_e32 v2, v2
	v_and_b32_e32 v31, 0xffff0000, v6
	v_mul_f32_e32 v6, 0xbfb8aa3b, v31
	v_exp_f32_e32 v6, v6
	v_add_f32_e32 v2, 1.0, v2
	v_rcp_f32_e32 v33, v2
	s_waitcnt lgkmcnt(0)
	v_mov_b32_e32 v28, v24
	v_lshlrev_b32_e32 v23, 16, v7
	v_add_f32_e32 v6, 1.0, v6
	v_pk_mul_f32 v[28:29], v[32:33], v[28:29]
	v_mov_b32_e32 v30, v25
	v_mul_f32_e32 v2, v28, v29
	v_rcp_f32_e32 v29, v6
	v_mul_f32_e32 v6, 0xbfb8aa3b, v23
	v_exp_f32_e32 v6, v6
	v_mul_f32_e32 v28, v34, v15
	v_and_b32_e32 v7, 0xffff0000, v7
	v_pk_mul_f32 v[24:25], v[28:29], v[30:31]
	v_add_f32_e32 v6, 1.0, v6
	v_mul_f32_e32 v28, v24, v25
	v_rcp_f32_e32 v25, v6
	v_mul_f32_e32 v6, 0xbfb8aa3b, v7
	v_exp_f32_e32 v6, v6
	v_mul_f32_e32 v24, v22, v15
	v_mov_b32_e32 v22, v26
	v_pk_mul_f32 v[22:23], v[24:25], v[22:23]
	v_add_f32_e32 v6, 1.0, v6
	v_rcp_f32_e32 v21, v6
	v_mov_b32_e32 v6, v27
	v_mul_f32_e32 v22, v22, v23
	v_mul_f32_e32 v30, v16, v15
	v_pk_mul_f32 v[6:7], v[20:21], v[6:7]
	s_nop 0
	v_mul_f32_e32 v7, v6, v7
	v_cvt_pk_bf16_f32 v6, v2, v28
	v_cvt_pk_bf16_f32 v7, v22, v7
	global_store_dwordx2 v[4:5], v[6:7], off offset:208
	v_mov_b32_e32 v6, v248
	v_mov_b32_e32 v7, v249
	s_nop 0
	ds_read_b128 v[20:23], v219 offset:448
	v_lshlrev_b32_e32 v25, 16, v6
	v_mul_f32_e32 v2, 0xbfb8aa3b, v25
	v_exp_f32_e32 v2, v2
	v_and_b32_e32 v27, 0xffff0000, v6
	v_mul_f32_e32 v6, 0xbfb8aa3b, v27
	v_exp_f32_e32 v6, v6
	v_add_f32_e32 v2, 1.0, v2
	v_rcp_f32_e32 v31, v2
	s_waitcnt lgkmcnt(0)
	v_mov_b32_e32 v24, v20
	v_lshlrev_b32_e32 v29, 16, v7
	v_add_f32_e32 v6, 1.0, v6
	v_pk_mul_f32 v[24:25], v[30:31], v[24:25]
	v_mov_b32_e32 v26, v21
	v_mul_f32_e32 v2, v24, v25
	v_rcp_f32_e32 v25, v6
	v_mul_f32_e32 v6, 0xbfb8aa3b, v29
	v_exp_f32_e32 v6, v6
	v_mul_f32_e32 v24, v14, v15
	v_and_b32_e32 v7, 0xffff0000, v7
	v_pk_mul_f32 v[20:21], v[24:25], v[26:27]
	v_add_f32_e32 v6, 1.0, v6
	v_mul_f32_e32 v14, v20, v21
	v_rcp_f32_e32 v21, v6
	v_mul_f32_e32 v6, 0xbfb8aa3b, v7
	v_exp_f32_e32 v6, v6
	v_mul_f32_e32 v20, v13, v15
	v_mov_b32_e32 v28, v22
	v_pk_mul_f32 v[20:21], v[20:21], v[28:29]
	v_add_f32_e32 v6, 1.0, v6
	v_rcp_f32_e32 v13, v6
	v_mov_b32_e32 v6, v23
	v_mul_f32_e32 v16, v20, v21
	v_mul_f32_e32 v24, v11, v15
	v_pk_mul_f32 v[6:7], v[12:13], v[6:7]
	s_nop 0
	v_mul_f32_e32 v7, v6, v7
	v_cvt_pk_bf16_f32 v6, v2, v14
	v_cvt_pk_bf16_f32 v7, v16, v7
	global_store_dwordx2 v[4:5], v[6:7], off offset:224
	v_mov_b32_e32 v6, v250
	v_mov_b32_e32 v7, v251
	s_nop 0
	ds_read_b128 v[16:19], v219 offset:480
	v_and_b32_e32 v21, 0xffff0000, v6
	v_lshlrev_b32_e32 v13, 16, v6
	v_mul_f32_e32 v6, 0xbfb8aa3b, v21
	v_mul_f32_e32 v2, 0xbfb8aa3b, v13
	v_exp_f32_e32 v6, v6
	v_exp_f32_e32 v2, v2
	v_lshlrev_b32_e32 v23, 16, v7
	s_waitcnt lgkmcnt(0)
	v_mov_b32_e32 v12, v16
	v_add_f32_e32 v6, 1.0, v6
	v_add_f32_e32 v2, 1.0, v2
	v_rcp_f32_e32 v11, v6
	v_mul_f32_e32 v6, 0xbfb8aa3b, v23
	v_rcp_f32_e32 v25, v2
	v_exp_f32_e32 v6, v6
	v_mov_b32_e32 v20, v17
	v_and_b32_e32 v7, 0xffff0000, v7
	v_pk_mul_f32 v[12:13], v[24:25], v[12:13]
	v_pk_mul_f32 v[10:11], v[10:11], v[20:21]
	v_add_f32_e32 v6, 1.0, v6
	v_mul_f32_e32 v2, v12, v13
	v_mul_f32_e32 v12, v10, v11
	v_rcp_f32_e32 v11, v6
	v_mul_f32_e32 v6, 0xbfb8aa3b, v7
	v_exp_f32_e32 v6, v6
	v_mul_f32_e32 v10, v9, v15
	v_mov_b32_e32 v22, v18
	v_pk_mul_f32 v[10:11], v[10:11], v[22:23]
	v_add_f32_e32 v6, 1.0, v6
	v_rcp_f32_e32 v9, v6
	v_mov_b32_e32 v6, v19
	v_mul_f32_e32 v10, v10, v11
	v_pk_mul_f32 v[6:7], v[8:9], v[6:7]
	s_nop 0
	v_mul_f32_e32 v7, v6, v7
	v_cvt_pk_bf16_f32 v6, v2, v12
	v_cvt_pk_bf16_f32 v7, v10, v7
	global_store_dwordx2 v[4:5], v[6:7], off offset:240
